# GEMM K-loops: inside each 16-MFMA group the two k-steps of one accumulator are issued back to back (dependent pairs adjacent; same accumulation order) to test accumulator forwarding energy
# speedup vs baseline: 1.0024x; 1.0008x over previous
.LBB0_540:
	s_add_u32 s22, s18, s20
	s_addc_u32 s23, s19, s21
	s_add_u32 s22, s22, 0x100
	s_addc_u32 s23, s23, 0
	s_add_u32 s49, s40, s20
	s_addc_u32 s56, s41, s21
	s_add_i32 s58, 0, 0x10000
	s_cmpk_eq_i32 s20, 0x700
	s_cselect_b32 s23, s15, s23
	s_cselect_b32 s22, s14, s22
	v_add_u32_e32 v149, s58, v147
	s_cselect_b32 s57, s17, s56
	s_cselect_b32 s56, s16, s49
	s_add_i32 s49, 0, 0x14000
	ds_read_b128 v[150:153], v149
	ds_read_b128 v[154:157], v149 offset:1024
	ds_read_b128 v[158:161], v149 offset:2048
	ds_read_b128 v[162:165], v149 offset:3072
	v_add_u32_e32 v149, s49, v147
	ds_read_b128 v[166:169], v149
	ds_read_b128 v[170:173], v149 offset:1024
	ds_read_b128 v[174:177], v149 offset:2048
	ds_read_b128 v[178:181], v149 offset:3072
	v_lshl_add_u64 v[220:221], v[142:143], 0, s[20:21]
	s_add_i32 m0, s27, 0xc000
	ds_read_b128 v[182:185], v148
	ds_read_b128 v[186:189], v148 offset:1024
	ds_read_b128 v[204:207], v148 offset:2048
	ds_read_b128 v[208:211], v148 offset:3072
	ds_read_b128 v[212:215], v148 offset:4096
	ds_read_b128 v[216:219], v148 offset:5120
	ds_read_b128 v[230:233], v148 offset:6144
	ds_read_b128 v[234:237], v148 offset:7168
	global_load_lds_dwordx4 v[220:221], off
	v_lshl_add_u64 v[220:221], v[144:145], 0, s[20:21]
	s_add_i32 m0, s27, 0xe000
	s_nop 0
	global_load_lds_dwordx4 v[220:221], off
	s_waitcnt vmcnt(8)
	s_waitcnt lgkmcnt(0)
	s_barrier
	s_setprio 1
	s_waitcnt lgkmcnt(0)
	v_mfma_f32_16x16x32_bf16 v[126:129], v[150:153], v[182:185], v[126:129]
	v_mfma_f32_16x16x32_bf16 v[126:129], v[154:157], v[186:189], v[126:129]
	v_mfma_f32_16x16x32_bf16 v[118:121], v[158:161], v[182:185], v[118:121]
	v_mfma_f32_16x16x32_bf16 v[118:121], v[162:165], v[186:189], v[118:121]
	v_mfma_f32_16x16x32_bf16 v[110:113], v[150:153], v[204:207], v[110:113]
	v_mfma_f32_16x16x32_bf16 v[110:113], v[154:157], v[208:211], v[110:113]
	v_mfma_f32_16x16x32_bf16 v[102:105], v[158:161], v[204:207], v[102:105]
	v_mfma_f32_16x16x32_bf16 v[102:105], v[162:165], v[208:211], v[102:105]
	v_mfma_f32_16x16x32_bf16 v[94:97], v[150:153], v[212:215], v[94:97]
	v_mfma_f32_16x16x32_bf16 v[94:97], v[154:157], v[216:219], v[94:97]
	v_mfma_f32_16x16x32_bf16 v[86:89], v[158:161], v[212:215], v[86:89]
	v_mfma_f32_16x16x32_bf16 v[86:89], v[162:165], v[216:219], v[86:89]
	v_mfma_f32_16x16x32_bf16 v[78:81], v[150:153], v[230:233], v[78:81]
	v_mfma_f32_16x16x32_bf16 v[78:81], v[154:157], v[234:237], v[78:81]
	v_mfma_f32_16x16x32_bf16 v[70:73], v[158:161], v[230:233], v[70:73]
	v_mfma_f32_16x16x32_bf16 v[70:73], v[162:165], v[234:237], v[70:73]
	s_setprio 0
	s_setprio 1
	v_mfma_f32_16x16x32_bf16 v[122:125], v[166:169], v[182:185], v[122:125]
	v_mfma_f32_16x16x32_bf16 v[122:125], v[170:173], v[186:189], v[122:125]
	v_mfma_f32_16x16x32_bf16 v[114:117], v[174:177], v[182:185], v[114:117]
	v_mfma_f32_16x16x32_bf16 v[114:117], v[178:181], v[186:189], v[114:117]
	v_mfma_f32_16x16x32_bf16 v[106:109], v[166:169], v[204:207], v[106:109]
	v_mfma_f32_16x16x32_bf16 v[106:109], v[170:173], v[208:211], v[106:109]
	v_mfma_f32_16x16x32_bf16 v[98:101], v[174:177], v[204:207], v[98:101]
	v_mfma_f32_16x16x32_bf16 v[98:101], v[178:181], v[208:211], v[98:101]
	v_mfma_f32_16x16x32_bf16 v[90:93], v[166:169], v[212:215], v[90:93]
	v_mfma_f32_16x16x32_bf16 v[90:93], v[170:173], v[216:219], v[90:93]
	v_mfma_f32_16x16x32_bf16 v[82:85], v[174:177], v[212:215], v[82:85]
	v_mfma_f32_16x16x32_bf16 v[82:85], v[178:181], v[216:219], v[82:85]
	v_mfma_f32_16x16x32_bf16 v[74:77], v[166:169], v[230:233], v[74:77]
	v_mfma_f32_16x16x32_bf16 v[74:77], v[170:173], v[234:237], v[74:77]
	v_mfma_f32_16x16x32_bf16 v[66:69], v[174:177], v[230:233], v[66:69]
	v_mfma_f32_16x16x32_bf16 v[66:69], v[178:181], v[234:237], v[66:69]
	s_setprio 0
	s_barrier
	s_add_i32 s58, s58, s25
	v_lshl_add_u64 v[220:221], s[56:57], 0, v[134:135]
	s_mov_b32 m0, s58
	ds_read_b128 v[182:185], v148 offset:16384
	ds_read_b128 v[186:189], v148 offset:17408
	ds_read_b128 v[204:207], v148 offset:18432
	ds_read_b128 v[208:211], v148 offset:19456
	ds_read_b128 v[212:215], v148 offset:20480
	ds_read_b128 v[216:219], v148 offset:21504
	ds_read_b128 v[230:233], v148 offset:22528
	ds_read_b128 v[234:237], v148 offset:23552
	global_load_lds_dwordx4 v[220:221], off
	s_add_i32 m0, s58, 0x2000
	v_lshl_add_u64 v[238:239], s[56:57], 0, v[130:131]
	s_add_u32 s56, s56, s4
	s_addc_u32 s57, s57, s5
	s_add_i32 s49, s49, s25
	global_load_lds_dwordx4 v[238:239], off
	v_lshl_add_u64 v[240:241], s[56:57], 0, v[134:135]
	s_mov_b32 m0, s49
	v_lshl_add_u64 v[242:243], s[56:57], 0, v[130:131]
	global_load_lds_dwordx4 v[240:241], off
	s_add_i32 m0, s49, 0x2000
	v_lshl_add_u64 v[244:245], s[22:23], 0, v[136:137]
	global_load_lds_dwordx4 v[242:243], off
	s_mov_b32 m0, s27
	v_lshl_add_u64 v[246:247], s[22:23], 0, v[132:133]
	global_load_lds_dwordx4 v[244:245], off
	s_mov_b32 m0, s28
	s_nop 0
	global_load_lds_dwordx4 v[246:247], off
	s_waitcnt vmcnt(8)
	s_waitcnt lgkmcnt(0)
	s_barrier
	s_setprio 1
	s_waitcnt lgkmcnt(0)
	v_mfma_f32_16x16x32_bf16 v[62:65], v[150:153], v[182:185], v[62:65]
	v_mfma_f32_16x16x32_bf16 v[62:65], v[154:157], v[186:189], v[62:65]
	v_mfma_f32_16x16x32_bf16 v[54:57], v[158:161], v[182:185], v[54:57]
	v_mfma_f32_16x16x32_bf16 v[54:57], v[162:165], v[186:189], v[54:57]
	v_mfma_f32_16x16x32_bf16 v[46:49], v[150:153], v[204:207], v[46:49]
	v_mfma_f32_16x16x32_bf16 v[46:49], v[154:157], v[208:211], v[46:49]
	v_mfma_f32_16x16x32_bf16 v[38:41], v[158:161], v[204:207], v[38:41]
	v_mfma_f32_16x16x32_bf16 v[38:41], v[162:165], v[208:211], v[38:41]
	v_mfma_f32_16x16x32_bf16 v[30:33], v[150:153], v[212:215], v[30:33]
	v_mfma_f32_16x16x32_bf16 v[30:33], v[154:157], v[216:219], v[30:33]
	v_mfma_f32_16x16x32_bf16 v[22:25], v[158:161], v[212:215], v[22:25]
	v_mfma_f32_16x16x32_bf16 v[22:25], v[162:165], v[216:219], v[22:25]
	v_mfma_f32_16x16x32_bf16 v[14:17], v[150:153], v[230:233], v[14:17]
	v_mfma_f32_16x16x32_bf16 v[14:17], v[154:157], v[234:237], v[14:17]
	v_mfma_f32_16x16x32_bf16 v[6:9], v[158:161], v[230:233], v[6:9]
	v_mfma_f32_16x16x32_bf16 v[6:9], v[162:165], v[234:237], v[6:9]
	s_setprio 0
	s_setprio 1
	v_mfma_f32_16x16x32_bf16 v[58:61], v[166:169], v[182:185], v[58:61]
	v_mfma_f32_16x16x32_bf16 v[58:61], v[170:173], v[186:189], v[58:61]
	v_mfma_f32_16x16x32_bf16 v[50:53], v[174:177], v[182:185], v[50:53]
	v_mfma_f32_16x16x32_bf16 v[50:53], v[178:181], v[186:189], v[50:53]
	v_mfma_f32_16x16x32_bf16 v[42:45], v[166:169], v[204:207], v[42:45]
	v_mfma_f32_16x16x32_bf16 v[42:45], v[170:173], v[208:211], v[42:45]
	v_mfma_f32_16x16x32_bf16 v[34:37], v[174:177], v[204:207], v[34:37]
	v_mfma_f32_16x16x32_bf16 v[34:37], v[178:181], v[208:211], v[34:37]
	v_mfma_f32_16x16x32_bf16 v[26:29], v[166:169], v[212:215], v[26:29]
	v_mfma_f32_16x16x32_bf16 v[26:29], v[170:173], v[216:219], v[26:29]
	v_mfma_f32_16x16x32_bf16 v[18:21], v[174:177], v[212:215], v[18:21]
	v_mfma_f32_16x16x32_bf16 v[18:21], v[178:181], v[216:219], v[18:21]
	v_mfma_f32_16x16x32_bf16 v[10:13], v[166:169], v[230:233], v[10:13]
	v_mfma_f32_16x16x32_bf16 v[10:13], v[170:173], v[234:237], v[10:13]
	v_mfma_f32_16x16x32_bf16 v[2:5], v[174:177], v[230:233], v[2:5]
	v_mfma_f32_16x16x32_bf16 v[2:5], v[178:181], v[234:237], v[2:5]
	s_setprio 0
	s_barrier
	s_add_i32 s49, 0, 0x18000
	v_add_u32_e32 v149, s49, v147
	s_add_i32 s56, 0, 0x1c000
	ds_read_b128 v[150:153], v149
	ds_read_b128 v[154:157], v149 offset:1024
	ds_read_b128 v[158:161], v149 offset:2048
	ds_read_b128 v[162:165], v149 offset:3072
	v_add_u32_e32 v149, s56, v147
	ds_read_b128 v[166:169], v149
	ds_read_b128 v[170:173], v149 offset:1024
	ds_read_b128 v[174:177], v149 offset:2048
	ds_read_b128 v[178:181], v149 offset:3072
	s_add_u32 s22, s22, s4
	s_addc_u32 s23, s23, s5
	s_mov_b32 m0, s29
	v_lshl_add_u64 v[248:249], s[22:23], 0, v[136:137]
	ds_read_b128 v[182:185], v148 offset:32768
	ds_read_b128 v[186:189], v148 offset:33792
	ds_read_b128 v[204:207], v148 offset:34816
	ds_read_b128 v[208:211], v148 offset:35840
	ds_read_b128 v[212:215], v148 offset:36864
	ds_read_b128 v[216:219], v148 offset:37888
	ds_read_b128 v[230:233], v148 offset:38912
	ds_read_b128 v[234:237], v148 offset:39936
	global_load_lds_dwordx4 v[248:249], off
	v_lshl_add_u64 v[248:249], s[22:23], 0, v[132:133]
	s_mov_b32 m0, s30
	s_nop 0
	global_load_lds_dwordx4 v[248:249], off
	s_waitcnt vmcnt(8)
	s_waitcnt lgkmcnt(0)
	s_barrier
	s_setprio 1
	s_waitcnt lgkmcnt(0)
	v_mfma_f32_16x16x32_bf16 v[126:129], v[150:153], v[182:185], v[126:129]
	v_mfma_f32_16x16x32_bf16 v[126:129], v[154:157], v[186:189], v[126:129]
	v_mfma_f32_16x16x32_bf16 v[118:121], v[158:161], v[182:185], v[118:121]
	v_mfma_f32_16x16x32_bf16 v[118:121], v[162:165], v[186:189], v[118:121]
	v_mfma_f32_16x16x32_bf16 v[110:113], v[150:153], v[204:207], v[110:113]
	v_mfma_f32_16x16x32_bf16 v[110:113], v[154:157], v[208:211], v[110:113]
	v_mfma_f32_16x16x32_bf16 v[102:105], v[158:161], v[204:207], v[102:105]
	v_mfma_f32_16x16x32_bf16 v[102:105], v[162:165], v[208:211], v[102:105]
	v_mfma_f32_16x16x32_bf16 v[94:97], v[150:153], v[212:215], v[94:97]
	v_mfma_f32_16x16x32_bf16 v[94:97], v[154:157], v[216:219], v[94:97]
	v_mfma_f32_16x16x32_bf16 v[86:89], v[158:161], v[212:215], v[86:89]
	v_mfma_f32_16x16x32_bf16 v[86:89], v[162:165], v[216:219], v[86:89]
	v_mfma_f32_16x16x32_bf16 v[78:81], v[150:153], v[230:233], v[78:81]
	v_mfma_f32_16x16x32_bf16 v[78:81], v[154:157], v[234:237], v[78:81]
	v_mfma_f32_16x16x32_bf16 v[70:73], v[158:161], v[230:233], v[70:73]
	v_mfma_f32_16x16x32_bf16 v[70:73], v[162:165], v[234:237], v[70:73]
	s_setprio 0
	s_setprio 1
	v_mfma_f32_16x16x32_bf16 v[122:125], v[166:169], v[182:185], v[122:125]
	v_mfma_f32_16x16x32_bf16 v[122:125], v[170:173], v[186:189], v[122:125]
	v_mfma_f32_16x16x32_bf16 v[114:117], v[174:177], v[182:185], v[114:117]
	v_mfma_f32_16x16x32_bf16 v[114:117], v[178:181], v[186:189], v[114:117]
	v_mfma_f32_16x16x32_bf16 v[106:109], v[166:169], v[204:207], v[106:109]
	v_mfma_f32_16x16x32_bf16 v[106:109], v[170:173], v[208:211], v[106:109]
	v_mfma_f32_16x16x32_bf16 v[98:101], v[174:177], v[204:207], v[98:101]
	v_mfma_f32_16x16x32_bf16 v[98:101], v[178:181], v[208:211], v[98:101]
	v_mfma_f32_16x16x32_bf16 v[90:93], v[166:169], v[212:215], v[90:93]
	v_mfma_f32_16x16x32_bf16 v[90:93], v[170:173], v[216:219], v[90:93]
	v_mfma_f32_16x16x32_bf16 v[82:85], v[174:177], v[212:215], v[82:85]
	v_mfma_f32_16x16x32_bf16 v[82:85], v[178:181], v[216:219], v[82:85]
	v_mfma_f32_16x16x32_bf16 v[74:77], v[166:169], v[230:233], v[74:77]
	v_mfma_f32_16x16x32_bf16 v[74:77], v[170:173], v[234:237], v[74:77]
	v_mfma_f32_16x16x32_bf16 v[66:69], v[174:177], v[230:233], v[66:69]
	v_mfma_f32_16x16x32_bf16 v[66:69], v[178:181], v[234:237], v[66:69]
	s_setprio 0
	s_barrier
	s_add_i32 s22, s49, s25
	v_lshl_add_u64 v[220:221], v[220:221], 0, s[68:69]
	s_mov_b32 m0, s22
	ds_read_b128 v[182:185], v148 offset:49152
	ds_read_b128 v[186:189], v148 offset:50176
	ds_read_b128 v[204:207], v148 offset:51200
	ds_read_b128 v[208:211], v148 offset:52224
	ds_read_b128 v[212:215], v148 offset:53248
	ds_read_b128 v[216:219], v148 offset:54272
	ds_read_b128 v[230:233], v148 offset:55296
	ds_read_b128 v[234:237], v148 offset:56320
	global_load_lds_dwordx4 v[220:221], off
	v_lshl_add_u64 v[220:221], v[238:239], 0, s[68:69]
	s_add_i32 m0, s22, 0x2000
	s_add_i32 s22, s56, s25
	global_load_lds_dwordx4 v[220:221], off
	v_lshl_add_u64 v[220:221], v[240:241], 0, s[68:69]
	s_mov_b32 m0, s22
	s_nop 0
	global_load_lds_dwordx4 v[220:221], off
	v_lshl_add_u64 v[220:221], v[242:243], 0, s[68:69]
	s_add_i32 m0, s22, 0x2000
	s_nop 0
	global_load_lds_dwordx4 v[220:221], off
	v_lshl_add_u64 v[220:221], v[244:245], 0, s[68:69]
	s_mov_b32 m0, s31
	s_nop 0
	global_load_lds_dwordx4 v[220:221], off
	v_lshl_add_u64 v[220:221], v[246:247], 0, s[68:69]
	s_mov_b32 m0, s33
	s_nop 0
	global_load_lds_dwordx4 v[220:221], off
	s_waitcnt vmcnt(8)
	s_waitcnt lgkmcnt(0)
	s_barrier
	s_setprio 1
	s_waitcnt lgkmcnt(0)
	v_mfma_f32_16x16x32_bf16 v[62:65], v[150:153], v[182:185], v[62:65]
	v_mfma_f32_16x16x32_bf16 v[62:65], v[154:157], v[186:189], v[62:65]
	v_mfma_f32_16x16x32_bf16 v[54:57], v[158:161], v[182:185], v[54:57]
	v_mfma_f32_16x16x32_bf16 v[54:57], v[162:165], v[186:189], v[54:57]
	v_mfma_f32_16x16x32_bf16 v[46:49], v[150:153], v[204:207], v[46:49]
	v_mfma_f32_16x16x32_bf16 v[46:49], v[154:157], v[208:211], v[46:49]
	v_mfma_f32_16x16x32_bf16 v[38:41], v[158:161], v[204:207], v[38:41]
	v_mfma_f32_16x16x32_bf16 v[38:41], v[162:165], v[208:211], v[38:41]
	v_mfma_f32_16x16x32_bf16 v[30:33], v[150:153], v[212:215], v[30:33]
	v_mfma_f32_16x16x32_bf16 v[30:33], v[154:157], v[216:219], v[30:33]
	v_mfma_f32_16x16x32_bf16 v[22:25], v[158:161], v[212:215], v[22:25]
	v_mfma_f32_16x16x32_bf16 v[22:25], v[162:165], v[216:219], v[22:25]
	v_mfma_f32_16x16x32_bf16 v[14:17], v[150:153], v[230:233], v[14:17]
	v_mfma_f32_16x16x32_bf16 v[14:17], v[154:157], v[234:237], v[14:17]
	v_mfma_f32_16x16x32_bf16 v[6:9], v[158:161], v[230:233], v[6:9]
	v_mfma_f32_16x16x32_bf16 v[6:9], v[162:165], v[234:237], v[6:9]
	s_setprio 0
	s_setprio 1
	v_mfma_f32_16x16x32_bf16 v[58:61], v[166:169], v[182:185], v[58:61]
	v_mfma_f32_16x16x32_bf16 v[58:61], v[170:173], v[186:189], v[58:61]
	v_mfma_f32_16x16x32_bf16 v[50:53], v[174:177], v[182:185], v[50:53]
	v_mfma_f32_16x16x32_bf16 v[50:53], v[178:181], v[186:189], v[50:53]
	v_mfma_f32_16x16x32_bf16 v[42:45], v[166:169], v[204:207], v[42:45]
	v_mfma_f32_16x16x32_bf16 v[42:45], v[170:173], v[208:211], v[42:45]
	v_mfma_f32_16x16x32_bf16 v[34:37], v[174:177], v[204:207], v[34:37]
	v_mfma_f32_16x16x32_bf16 v[34:37], v[178:181], v[208:211], v[34:37]
	v_mfma_f32_16x16x32_bf16 v[26:29], v[166:169], v[212:215], v[26:29]
	v_mfma_f32_16x16x32_bf16 v[26:29], v[170:173], v[216:219], v[26:29]
	v_mfma_f32_16x16x32_bf16 v[18:21], v[174:177], v[212:215], v[18:21]
	v_mfma_f32_16x16x32_bf16 v[18:21], v[178:181], v[216:219], v[18:21]
	v_mfma_f32_16x16x32_bf16 v[10:13], v[166:169], v[230:233], v[10:13]
	v_mfma_f32_16x16x32_bf16 v[10:13], v[170:173], v[234:237], v[10:13]
	v_mfma_f32_16x16x32_bf16 v[2:5], v[174:177], v[230:233], v[2:5]
	v_mfma_f32_16x16x32_bf16 v[2:5], v[178:181], v[234:237], v[2:5]
	s_setprio 0
	s_barrier
	s_add_i32 s48, s48, 2
	s_add_u32 s20, s20, 0x100
	s_addc_u32 s21, s21, 0
	s_cmp_gt_u32 s48, 13
	s_cbranch_scc0 .LBB0_540
	s_and_b64 vcc, exec, s[12:13]
	s_cbranch_vccz .LBB0_543
	s_barrier

.LBB0_590:
	s_add_i32 s86, s26, 2
	s_add_u32 s74, s24, 0x80
	s_addc_u32 s27, s25, 0
	s_add_i32 s87, 0, 0x10000
	s_cmp_eq_u32 s19, s26
	s_cselect_b32 s27, s21, s27
	s_cselect_b32 s26, s20, s74
	v_add_u32_e32 v148, s87, v152
	s_cselect_b32 s75, s23, s29
	s_cselect_b32 s74, s22, s28
	s_add_i32 s88, 0, 0x14000
	ds_read_b128 v[130:133], v148
	ds_read_b128 v[144:147], v148 offset:1024
	ds_read_b128 v[154:157], v148 offset:2048
	ds_read_b128 v[158:161], v148 offset:3072
	v_add_u32_e32 v148, s88, v152
	ds_read_b128 v[162:165], v148
	ds_read_b128 v[166:169], v148 offset:1024
	ds_read_b128 v[170:173], v148 offset:2048
	ds_read_b128 v[174:177], v148 offset:3072
	v_lshl_add_u64 v[148:149], s[24:25], 0, v[140:141]
	s_add_i32 m0, s34, 0xc000
	ds_read_b128 v[178:181], v153
	ds_read_b128 v[182:185], v153 offset:1024
	ds_read_b128 v[186:189], v153 offset:2048
	ds_read_b128 v[204:207], v153 offset:3072
	ds_read_b128 v[208:211], v153 offset:4096
	ds_read_b128 v[212:215], v153 offset:5120
	ds_read_b128 v[216:219], v153 offset:6144
	ds_read_b128 v[230:233], v153 offset:7168
	global_load_lds_dwordx4 v[148:149], off
	v_lshl_add_u64 v[148:149], s[24:25], 0, v[142:143]
	s_add_i32 m0, s34, 0xe000
	s_nop 0
	global_load_lds_dwordx4 v[148:149], off
	s_waitcnt vmcnt(8)
	s_waitcnt lgkmcnt(0)
	s_barrier
	s_setprio 1
	s_waitcnt lgkmcnt(0)
	v_mfma_f32_16x16x32_bf16 v[126:129], v[130:133], v[178:181], v[126:129]
	v_mfma_f32_16x16x32_bf16 v[126:129], v[144:147], v[182:185], v[126:129]
	v_mfma_f32_16x16x32_bf16 v[122:125], v[154:157], v[178:181], v[122:125]
	v_mfma_f32_16x16x32_bf16 v[122:125], v[158:161], v[182:185], v[122:125]
	v_mfma_f32_16x16x32_bf16 v[110:113], v[130:133], v[186:189], v[110:113]
	v_mfma_f32_16x16x32_bf16 v[110:113], v[144:147], v[204:207], v[110:113]
	v_mfma_f32_16x16x32_bf16 v[106:109], v[154:157], v[186:189], v[106:109]
	v_mfma_f32_16x16x32_bf16 v[106:109], v[158:161], v[204:207], v[106:109]
	v_mfma_f32_16x16x32_bf16 v[94:97], v[130:133], v[208:211], v[94:97]
	v_mfma_f32_16x16x32_bf16 v[94:97], v[144:147], v[212:215], v[94:97]
	v_mfma_f32_16x16x32_bf16 v[90:93], v[154:157], v[208:211], v[90:93]
	v_mfma_f32_16x16x32_bf16 v[90:93], v[158:161], v[212:215], v[90:93]
	v_mfma_f32_16x16x32_bf16 v[78:81], v[130:133], v[216:219], v[78:81]
	v_mfma_f32_16x16x32_bf16 v[78:81], v[144:147], v[230:233], v[78:81]
	v_mfma_f32_16x16x32_bf16 v[74:77], v[154:157], v[216:219], v[74:77]
	v_mfma_f32_16x16x32_bf16 v[74:77], v[158:161], v[230:233], v[74:77]
	s_setprio 0
	s_setprio 1
	v_mfma_f32_16x16x32_bf16 v[118:121], v[162:165], v[178:181], v[118:121]
	v_mfma_f32_16x16x32_bf16 v[118:121], v[166:169], v[182:185], v[118:121]
	v_mfma_f32_16x16x32_bf16 v[114:117], v[170:173], v[178:181], v[114:117]
	v_mfma_f32_16x16x32_bf16 v[114:117], v[174:177], v[182:185], v[114:117]
	v_mfma_f32_16x16x32_bf16 v[102:105], v[162:165], v[186:189], v[102:105]
	v_mfma_f32_16x16x32_bf16 v[102:105], v[166:169], v[204:207], v[102:105]
	v_mfma_f32_16x16x32_bf16 v[98:101], v[170:173], v[186:189], v[98:101]
	v_mfma_f32_16x16x32_bf16 v[98:101], v[174:177], v[204:207], v[98:101]
	v_mfma_f32_16x16x32_bf16 v[86:89], v[162:165], v[208:211], v[86:89]
	v_mfma_f32_16x16x32_bf16 v[86:89], v[166:169], v[212:215], v[86:89]
	v_mfma_f32_16x16x32_bf16 v[82:85], v[170:173], v[208:211], v[82:85]
	v_mfma_f32_16x16x32_bf16 v[82:85], v[174:177], v[212:215], v[82:85]
	v_mfma_f32_16x16x32_bf16 v[70:73], v[162:165], v[216:219], v[70:73]
	v_mfma_f32_16x16x32_bf16 v[70:73], v[166:169], v[230:233], v[70:73]
	v_mfma_f32_16x16x32_bf16 v[66:69], v[170:173], v[216:219], v[66:69]
	v_mfma_f32_16x16x32_bf16 v[66:69], v[174:177], v[230:233], v[66:69]
	s_setprio 0
	s_barrier
	s_add_i32 s87, s87, s33
	v_lshl_add_u64 v[148:149], s[74:75], 0, v[190:191]
	s_mov_b32 m0, s87
	ds_read_b128 v[178:181], v153 offset:16384
	ds_read_b128 v[182:185], v153 offset:17408
	ds_read_b128 v[186:189], v153 offset:18432
	ds_read_b128 v[204:207], v153 offset:19456
	ds_read_b128 v[208:211], v153 offset:20480
	ds_read_b128 v[212:215], v153 offset:21504
	ds_read_b128 v[216:219], v153 offset:22528
	ds_read_b128 v[230:233], v153 offset:23552
	global_load_lds_dwordx4 v[148:149], off
	s_add_i32 m0, s87, 0x2000
	v_lshl_add_u64 v[220:221], s[74:75], 0, v[138:139]
	s_add_u32 s74, s74, s8
	s_addc_u32 s75, s75, s9
	s_add_i32 s87, s88, s33
	global_load_lds_dwordx4 v[220:221], off
	v_lshl_add_u64 v[234:235], s[74:75], 0, v[190:191]
	s_mov_b32 m0, s87
	v_lshl_add_u64 v[236:237], s[74:75], 0, v[138:139]
	global_load_lds_dwordx4 v[234:235], off
	s_add_i32 m0, s87, 0x2000
	v_lshl_add_u64 v[238:239], s[26:27], 0, v[134:135]
	global_load_lds_dwordx4 v[236:237], off
	s_mov_b32 m0, s34
	v_lshl_add_u64 v[240:241], s[26:27], 0, v[136:137]
	global_load_lds_dwordx4 v[238:239], off
	s_mov_b32 m0, s35
	s_nop 0
	global_load_lds_dwordx4 v[240:241], off
	s_waitcnt vmcnt(8)
	s_waitcnt lgkmcnt(0)
	s_barrier
	s_setprio 1
	s_waitcnt lgkmcnt(0)
	v_mfma_f32_16x16x32_bf16 v[62:65], v[130:133], v[178:181], v[62:65]
	v_mfma_f32_16x16x32_bf16 v[62:65], v[144:147], v[182:185], v[62:65]
	v_mfma_f32_16x16x32_bf16 v[58:61], v[154:157], v[178:181], v[58:61]
	v_mfma_f32_16x16x32_bf16 v[58:61], v[158:161], v[182:185], v[58:61]
	v_mfma_f32_16x16x32_bf16 v[46:49], v[130:133], v[186:189], v[46:49]
	v_mfma_f32_16x16x32_bf16 v[46:49], v[144:147], v[204:207], v[46:49]
	v_mfma_f32_16x16x32_bf16 v[42:45], v[154:157], v[186:189], v[42:45]
	v_mfma_f32_16x16x32_bf16 v[42:45], v[158:161], v[204:207], v[42:45]
	v_mfma_f32_16x16x32_bf16 v[30:33], v[130:133], v[208:211], v[30:33]
	v_mfma_f32_16x16x32_bf16 v[30:33], v[144:147], v[212:215], v[30:33]
	v_mfma_f32_16x16x32_bf16 v[26:29], v[154:157], v[208:211], v[26:29]
	v_mfma_f32_16x16x32_bf16 v[26:29], v[158:161], v[212:215], v[26:29]
	v_mfma_f32_16x16x32_bf16 v[14:17], v[130:133], v[216:219], v[14:17]
	v_mfma_f32_16x16x32_bf16 v[14:17], v[144:147], v[230:233], v[14:17]
	v_mfma_f32_16x16x32_bf16 v[10:13], v[154:157], v[216:219], v[10:13]
	v_mfma_f32_16x16x32_bf16 v[10:13], v[158:161], v[230:233], v[10:13]
	s_setprio 0
	s_setprio 1
	v_mfma_f32_16x16x32_bf16 v[54:57], v[162:165], v[178:181], v[54:57]
	v_mfma_f32_16x16x32_bf16 v[54:57], v[166:169], v[182:185], v[54:57]
	v_mfma_f32_16x16x32_bf16 v[50:53], v[170:173], v[178:181], v[50:53]
	v_mfma_f32_16x16x32_bf16 v[50:53], v[174:177], v[182:185], v[50:53]
	v_mfma_f32_16x16x32_bf16 v[38:41], v[162:165], v[186:189], v[38:41]
	v_mfma_f32_16x16x32_bf16 v[38:41], v[166:169], v[204:207], v[38:41]
	v_mfma_f32_16x16x32_bf16 v[34:37], v[170:173], v[186:189], v[34:37]
	v_mfma_f32_16x16x32_bf16 v[34:37], v[174:177], v[204:207], v[34:37]
	v_mfma_f32_16x16x32_bf16 v[22:25], v[162:165], v[208:211], v[22:25]
	v_mfma_f32_16x16x32_bf16 v[22:25], v[166:169], v[212:215], v[22:25]
	v_mfma_f32_16x16x32_bf16 v[18:21], v[170:173], v[208:211], v[18:21]
	v_mfma_f32_16x16x32_bf16 v[18:21], v[174:177], v[212:215], v[18:21]
	v_mfma_f32_16x16x32_bf16 v[6:9], v[162:165], v[216:219], v[6:9]
	v_mfma_f32_16x16x32_bf16 v[6:9], v[166:169], v[230:233], v[6:9]
	v_mfma_f32_16x16x32_bf16 v[2:5], v[170:173], v[216:219], v[2:5]
	v_mfma_f32_16x16x32_bf16 v[2:5], v[174:177], v[230:233], v[2:5]
	s_setprio 0
	s_barrier
	s_add_i32 s74, 0, 0x18000
	s_add_i32 s75, 0, 0x1c000
	v_add_u32_e32 v158, s74, v152
	v_add_u32_e32 v174, s75, v152
	ds_read_b128 v[130:133], v158
	ds_read_b128 v[144:147], v158 offset:1024
	ds_read_b128 v[154:157], v158 offset:2048
	ds_read_b128 v[158:161], v158 offset:3072
	ds_read_b128 v[162:165], v174
	ds_read_b128 v[166:169], v174 offset:1024
	ds_read_b128 v[170:173], v174 offset:2048
	ds_read_b128 v[174:177], v174 offset:3072
	s_add_u32 s26, s26, s8
	s_addc_u32 s27, s27, s9
	s_mov_b32 m0, s36
	v_lshl_add_u64 v[242:243], s[26:27], 0, v[134:135]
	ds_read_b128 v[178:181], v153 offset:32768
	ds_read_b128 v[182:185], v153 offset:33792
	ds_read_b128 v[186:189], v153 offset:34816
	ds_read_b128 v[204:207], v153 offset:35840
	ds_read_b128 v[208:211], v153 offset:36864
	ds_read_b128 v[212:215], v153 offset:37888
	ds_read_b128 v[216:219], v153 offset:38912
	ds_read_b128 v[230:233], v153 offset:39936
	global_load_lds_dwordx4 v[242:243], off
	v_lshl_add_u64 v[242:243], s[26:27], 0, v[136:137]
	s_mov_b32 m0, s37
	s_nop 0
	global_load_lds_dwordx4 v[242:243], off
	s_waitcnt vmcnt(8)
	s_waitcnt lgkmcnt(0)
	s_barrier
	s_setprio 1
	s_waitcnt lgkmcnt(0)
	v_mfma_f32_16x16x32_bf16 v[126:129], v[130:133], v[178:181], v[126:129]
	v_mfma_f32_16x16x32_bf16 v[126:129], v[144:147], v[182:185], v[126:129]
	v_mfma_f32_16x16x32_bf16 v[122:125], v[154:157], v[178:181], v[122:125]
	v_mfma_f32_16x16x32_bf16 v[122:125], v[158:161], v[182:185], v[122:125]
	v_mfma_f32_16x16x32_bf16 v[110:113], v[130:133], v[186:189], v[110:113]
	v_mfma_f32_16x16x32_bf16 v[110:113], v[144:147], v[204:207], v[110:113]
	v_mfma_f32_16x16x32_bf16 v[106:109], v[154:157], v[186:189], v[106:109]
	v_mfma_f32_16x16x32_bf16 v[106:109], v[158:161], v[204:207], v[106:109]
	v_mfma_f32_16x16x32_bf16 v[94:97], v[130:133], v[208:211], v[94:97]
	v_mfma_f32_16x16x32_bf16 v[94:97], v[144:147], v[212:215], v[94:97]
	v_mfma_f32_16x16x32_bf16 v[90:93], v[154:157], v[208:211], v[90:93]
	v_mfma_f32_16x16x32_bf16 v[90:93], v[158:161], v[212:215], v[90:93]
	v_mfma_f32_16x16x32_bf16 v[78:81], v[130:133], v[216:219], v[78:81]
	v_mfma_f32_16x16x32_bf16 v[78:81], v[144:147], v[230:233], v[78:81]
	v_mfma_f32_16x16x32_bf16 v[74:77], v[154:157], v[216:219], v[74:77]
	v_mfma_f32_16x16x32_bf16 v[74:77], v[158:161], v[230:233], v[74:77]
	s_setprio 0
	s_setprio 1
	v_mfma_f32_16x16x32_bf16 v[118:121], v[162:165], v[178:181], v[118:121]
	v_mfma_f32_16x16x32_bf16 v[118:121], v[166:169], v[182:185], v[118:121]
	v_mfma_f32_16x16x32_bf16 v[114:117], v[170:173], v[178:181], v[114:117]
	v_mfma_f32_16x16x32_bf16 v[114:117], v[174:177], v[182:185], v[114:117]
	v_mfma_f32_16x16x32_bf16 v[102:105], v[162:165], v[186:189], v[102:105]
	v_mfma_f32_16x16x32_bf16 v[102:105], v[166:169], v[204:207], v[102:105]
	v_mfma_f32_16x16x32_bf16 v[98:101], v[170:173], v[186:189], v[98:101]
	v_mfma_f32_16x16x32_bf16 v[98:101], v[174:177], v[204:207], v[98:101]
	v_mfma_f32_16x16x32_bf16 v[86:89], v[162:165], v[208:211], v[86:89]
	v_mfma_f32_16x16x32_bf16 v[86:89], v[166:169], v[212:215], v[86:89]
	v_mfma_f32_16x16x32_bf16 v[82:85], v[170:173], v[208:211], v[82:85]
	v_mfma_f32_16x16x32_bf16 v[82:85], v[174:177], v[212:215], v[82:85]
	v_mfma_f32_16x16x32_bf16 v[70:73], v[162:165], v[216:219], v[70:73]
	v_mfma_f32_16x16x32_bf16 v[70:73], v[166:169], v[230:233], v[70:73]
	v_mfma_f32_16x16x32_bf16 v[66:69], v[170:173], v[216:219], v[66:69]
	v_mfma_f32_16x16x32_bf16 v[66:69], v[174:177], v[230:233], v[66:69]
	s_setprio 0
	s_barrier
	s_add_i32 s26, s74, s33
	v_lshl_add_u64 v[148:149], v[148:149], 0, s[68:69]
	s_mov_b32 m0, s26
	ds_read_b128 v[178:181], v153 offset:49152
	ds_read_b128 v[182:185], v153 offset:50176
	ds_read_b128 v[186:189], v153 offset:51200
	ds_read_b128 v[204:207], v153 offset:52224
	ds_read_b128 v[208:211], v153 offset:53248
	ds_read_b128 v[212:215], v153 offset:54272
	ds_read_b128 v[216:219], v153 offset:55296
	ds_read_b128 v[230:233], v153 offset:56320
	global_load_lds_dwordx4 v[148:149], off
	v_lshl_add_u64 v[148:149], v[220:221], 0, s[68:69]
	s_add_i32 m0, s26, 0x2000
	s_add_i32 s26, s75, s33
	global_load_lds_dwordx4 v[148:149], off
	v_lshl_add_u64 v[148:149], v[234:235], 0, s[68:69]
	s_mov_b32 m0, s26
	s_nop 0
	global_load_lds_dwordx4 v[148:149], off
	v_lshl_add_u64 v[148:149], v[236:237], 0, s[68:69]
	s_add_i32 m0, s26, 0x2000
	s_nop 0
	global_load_lds_dwordx4 v[148:149], off
	v_lshl_add_u64 v[148:149], v[238:239], 0, s[68:69]
	s_mov_b32 m0, s72
	s_nop 0
	global_load_lds_dwordx4 v[148:149], off
	v_lshl_add_u64 v[148:149], v[240:241], 0, s[68:69]
	s_mov_b32 m0, s78
	s_nop 0
	global_load_lds_dwordx4 v[148:149], off
	s_waitcnt vmcnt(8)
	s_waitcnt lgkmcnt(0)
	s_barrier
	s_setprio 1
	s_waitcnt lgkmcnt(0)
	v_mfma_f32_16x16x32_bf16 v[62:65], v[130:133], v[178:181], v[62:65]
	v_mfma_f32_16x16x32_bf16 v[62:65], v[144:147], v[182:185], v[62:65]
	v_mfma_f32_16x16x32_bf16 v[58:61], v[154:157], v[178:181], v[58:61]
	v_mfma_f32_16x16x32_bf16 v[58:61], v[158:161], v[182:185], v[58:61]
	v_mfma_f32_16x16x32_bf16 v[46:49], v[130:133], v[186:189], v[46:49]
	v_mfma_f32_16x16x32_bf16 v[46:49], v[144:147], v[204:207], v[46:49]
	v_mfma_f32_16x16x32_bf16 v[42:45], v[154:157], v[186:189], v[42:45]
	v_mfma_f32_16x16x32_bf16 v[42:45], v[158:161], v[204:207], v[42:45]
	v_mfma_f32_16x16x32_bf16 v[30:33], v[130:133], v[208:211], v[30:33]
	v_mfma_f32_16x16x32_bf16 v[30:33], v[144:147], v[212:215], v[30:33]
	v_mfma_f32_16x16x32_bf16 v[26:29], v[154:157], v[208:211], v[26:29]
	v_mfma_f32_16x16x32_bf16 v[26:29], v[158:161], v[212:215], v[26:29]
	v_mfma_f32_16x16x32_bf16 v[14:17], v[130:133], v[216:219], v[14:17]
	v_mfma_f32_16x16x32_bf16 v[14:17], v[144:147], v[230:233], v[14:17]
	v_mfma_f32_16x16x32_bf16 v[10:13], v[154:157], v[216:219], v[10:13]
	v_mfma_f32_16x16x32_bf16 v[10:13], v[158:161], v[230:233], v[10:13]
	s_setprio 0
	s_setprio 1
	v_mfma_f32_16x16x32_bf16 v[54:57], v[162:165], v[178:181], v[54:57]
	v_mfma_f32_16x16x32_bf16 v[54:57], v[166:169], v[182:185], v[54:57]
	v_mfma_f32_16x16x32_bf16 v[50:53], v[170:173], v[178:181], v[50:53]
	v_mfma_f32_16x16x32_bf16 v[50:53], v[174:177], v[182:185], v[50:53]
	v_mfma_f32_16x16x32_bf16 v[38:41], v[162:165], v[186:189], v[38:41]
	v_mfma_f32_16x16x32_bf16 v[38:41], v[166:169], v[204:207], v[38:41]
	v_mfma_f32_16x16x32_bf16 v[34:37], v[170:173], v[186:189], v[34:37]
	v_mfma_f32_16x16x32_bf16 v[34:37], v[174:177], v[204:207], v[34:37]
	v_mfma_f32_16x16x32_bf16 v[22:25], v[162:165], v[208:211], v[22:25]
	v_mfma_f32_16x16x32_bf16 v[22:25], v[166:169], v[212:215], v[22:25]
	v_mfma_f32_16x16x32_bf16 v[18:21], v[170:173], v[208:211], v[18:21]
	v_mfma_f32_16x16x32_bf16 v[18:21], v[174:177], v[212:215], v[18:21]
	v_mfma_f32_16x16x32_bf16 v[6:9], v[162:165], v[216:219], v[6:9]
	v_mfma_f32_16x16x32_bf16 v[6:9], v[166:169], v[230:233], v[6:9]
	v_mfma_f32_16x16x32_bf16 v[2:5], v[170:173], v[216:219], v[2:5]
	v_mfma_f32_16x16x32_bf16 v[2:5], v[174:177], v[230:233], v[2:5]
	s_setprio 0
	s_barrier
	s_add_u32 s24, s24, 0x100
	s_addc_u32 s25, s25, 0
	s_add_u32 s28, s28, 0x100
	s_addc_u32 s29, s29, 0
	s_cmp_ge_i32 s86, s85
	s_mov_b32 s26, s86
	s_cbranch_scc0 .LBB0_590
	s_and_b64 vcc, exec, s[16:17]
	s_cbranch_vccz .LBB0_593
	s_barrier

.LBB0_1658:
	s_add_u32 s10, s34, s44
	s_addc_u32 s11, s35, s45
	s_add_u32 s10, s10, 0x100
	s_addc_u32 s11, s11, 0
	s_add_u32 s72, s33, s44
	s_addc_u32 s74, s48, s45
	s_add_i32 s75, 0, 0x10000
	s_cmpk_eq_i32 s44, 0x700
	s_cselect_b32 s11, s29, s11
	s_cselect_b32 s10, s28, s10
	s_cselect_b32 s81, s31, s74
	s_cselect_b32 s80, s30, s72
	s_add_i32 s72, 0, 0x14000
	v_add_u32_e32 v146, s75, v184
	v_add_u32_e32 v158, s72, v184
	ds_read_b128 v[134:137], v146
	ds_read_b128 v[138:141], v146 offset:1024
	ds_read_b128 v[142:145], v146 offset:2048
	ds_read_b128 v[146:149], v146 offset:3072
	ds_read_b128 v[150:153], v158
	ds_read_b128 v[154:157], v158 offset:1024
	ds_read_b128 v[178:181], v158 offset:2048
	ds_read_b128 v[186:189], v158 offset:3072
	v_lshl_add_u64 v[158:159], v[130:131], 0, s[44:45]
	s_add_i32 m0, s14, 0xc000
	ds_read_b128 v[204:207], v185
	ds_read_b128 v[208:211], v185 offset:1024
	ds_read_b128 v[212:215], v185 offset:2048
	ds_read_b128 v[216:219], v185 offset:3072
	ds_read_b128 v[226:229], v185 offset:4096
	ds_read_b128 v[230:233], v185 offset:5120
	ds_read_b128 v[234:237], v185 offset:6144
	ds_read_b128 v[238:241], v185 offset:7168
	global_load_lds_dwordx4 v[158:159], off
	v_lshl_add_u64 v[158:159], v[132:133], 0, s[44:45]
	s_add_i32 m0, s14, 0xe000
	s_nop 0
	global_load_lds_dwordx4 v[158:159], off
	s_waitcnt vmcnt(8)
	s_waitcnt lgkmcnt(0)
	s_barrier
	s_setprio 1
	s_waitcnt lgkmcnt(0)
	v_mfma_f32_16x16x32_bf16 v[126:129], v[134:137], v[204:207], v[126:129]
	v_mfma_f32_16x16x32_bf16 v[126:129], v[138:141], v[208:211], v[126:129]
	v_mfma_f32_16x16x32_bf16 v[122:125], v[142:145], v[204:207], v[122:125]
	v_mfma_f32_16x16x32_bf16 v[122:125], v[146:149], v[208:211], v[122:125]
	v_mfma_f32_16x16x32_bf16 v[110:113], v[134:137], v[212:215], v[110:113]
	v_mfma_f32_16x16x32_bf16 v[110:113], v[138:141], v[216:219], v[110:113]
	v_mfma_f32_16x16x32_bf16 v[106:109], v[142:145], v[212:215], v[106:109]
	v_mfma_f32_16x16x32_bf16 v[106:109], v[146:149], v[216:219], v[106:109]
	v_mfma_f32_16x16x32_bf16 v[94:97], v[134:137], v[226:229], v[94:97]
	v_mfma_f32_16x16x32_bf16 v[94:97], v[138:141], v[230:233], v[94:97]
	v_mfma_f32_16x16x32_bf16 v[90:93], v[142:145], v[226:229], v[90:93]
	v_mfma_f32_16x16x32_bf16 v[90:93], v[146:149], v[230:233], v[90:93]
	v_mfma_f32_16x16x32_bf16 v[78:81], v[134:137], v[234:237], v[78:81]
	v_mfma_f32_16x16x32_bf16 v[78:81], v[138:141], v[238:241], v[78:81]
	v_mfma_f32_16x16x32_bf16 v[74:77], v[142:145], v[234:237], v[74:77]
	v_mfma_f32_16x16x32_bf16 v[74:77], v[146:149], v[238:241], v[74:77]
	s_setprio 0
	s_setprio 1
	v_mfma_f32_16x16x32_bf16 v[118:121], v[150:153], v[204:207], v[118:121]
	v_mfma_f32_16x16x32_bf16 v[118:121], v[154:157], v[208:211], v[118:121]
	v_mfma_f32_16x16x32_bf16 v[114:117], v[178:181], v[204:207], v[114:117]
	v_mfma_f32_16x16x32_bf16 v[114:117], v[186:189], v[208:211], v[114:117]
	v_mfma_f32_16x16x32_bf16 v[102:105], v[150:153], v[212:215], v[102:105]
	v_mfma_f32_16x16x32_bf16 v[102:105], v[154:157], v[216:219], v[102:105]
	v_mfma_f32_16x16x32_bf16 v[98:101], v[178:181], v[212:215], v[98:101]
	v_mfma_f32_16x16x32_bf16 v[98:101], v[186:189], v[216:219], v[98:101]
	v_mfma_f32_16x16x32_bf16 v[86:89], v[150:153], v[226:229], v[86:89]
	v_mfma_f32_16x16x32_bf16 v[86:89], v[154:157], v[230:233], v[86:89]
	v_mfma_f32_16x16x32_bf16 v[82:85], v[178:181], v[226:229], v[82:85]
	v_mfma_f32_16x16x32_bf16 v[82:85], v[186:189], v[230:233], v[82:85]
	v_mfma_f32_16x16x32_bf16 v[70:73], v[150:153], v[234:237], v[70:73]
	v_mfma_f32_16x16x32_bf16 v[70:73], v[154:157], v[238:241], v[70:73]
	v_mfma_f32_16x16x32_bf16 v[66:69], v[178:181], v[234:237], v[66:69]
	v_mfma_f32_16x16x32_bf16 v[66:69], v[186:189], v[238:241], v[66:69]
	s_setprio 0
	s_barrier
	s_add_i32 s74, s75, s82
	v_lshl_add_u64 v[158:159], s[80:81], 0, v[162:163]
	s_mov_b32 m0, s74
	ds_read_b128 v[204:207], v185 offset:16384
	ds_read_b128 v[208:211], v185 offset:17408
	ds_read_b128 v[212:215], v185 offset:18432
	ds_read_b128 v[216:219], v185 offset:19456
	ds_read_b128 v[226:229], v185 offset:20480
	ds_read_b128 v[230:233], v185 offset:21504
	ds_read_b128 v[234:237], v185 offset:22528
	ds_read_b128 v[238:241], v185 offset:23552
	global_load_lds_dwordx4 v[158:159], off
	s_add_i32 m0, s74, 0x2000
	v_lshl_add_u64 v[182:183], s[80:81], 0, v[166:167]
	s_add_u32 s80, s80, s4
	s_addc_u32 s81, s81, s5
	s_add_i32 s72, s72, s82
	global_load_lds_dwordx4 v[182:183], off
	v_lshl_add_u64 v[220:221], s[80:81], 0, v[162:163]
	s_mov_b32 m0, s72
	v_lshl_add_u64 v[242:243], s[80:81], 0, v[166:167]
	global_load_lds_dwordx4 v[220:221], off
	s_add_i32 m0, s72, 0x2000
	v_lshl_add_u64 v[244:245], s[10:11], 0, v[160:161]
	global_load_lds_dwordx4 v[242:243], off
	s_mov_b32 m0, s14
	v_lshl_add_u64 v[246:247], s[10:11], 0, v[164:165]
	global_load_lds_dwordx4 v[244:245], off
	s_mov_b32 m0, s15
	s_nop 0
	global_load_lds_dwordx4 v[246:247], off
	s_waitcnt vmcnt(8)
	s_waitcnt lgkmcnt(0)
	s_barrier
	s_setprio 1
	s_waitcnt lgkmcnt(0)
	v_mfma_f32_16x16x32_bf16 v[62:65], v[134:137], v[204:207], v[62:65]
	v_mfma_f32_16x16x32_bf16 v[62:65], v[138:141], v[208:211], v[62:65]
	v_mfma_f32_16x16x32_bf16 v[58:61], v[142:145], v[204:207], v[58:61]
	v_mfma_f32_16x16x32_bf16 v[58:61], v[146:149], v[208:211], v[58:61]
	v_mfma_f32_16x16x32_bf16 v[46:49], v[134:137], v[212:215], v[46:49]
	v_mfma_f32_16x16x32_bf16 v[46:49], v[138:141], v[216:219], v[46:49]
	v_mfma_f32_16x16x32_bf16 v[42:45], v[142:145], v[212:215], v[42:45]
	v_mfma_f32_16x16x32_bf16 v[42:45], v[146:149], v[216:219], v[42:45]
	v_mfma_f32_16x16x32_bf16 v[30:33], v[134:137], v[226:229], v[30:33]
	v_mfma_f32_16x16x32_bf16 v[30:33], v[138:141], v[230:233], v[30:33]
	v_mfma_f32_16x16x32_bf16 v[26:29], v[142:145], v[226:229], v[26:29]
	v_mfma_f32_16x16x32_bf16 v[26:29], v[146:149], v[230:233], v[26:29]
	v_mfma_f32_16x16x32_bf16 v[14:17], v[134:137], v[234:237], v[14:17]
	v_mfma_f32_16x16x32_bf16 v[14:17], v[138:141], v[238:241], v[14:17]
	v_mfma_f32_16x16x32_bf16 v[10:13], v[142:145], v[234:237], v[10:13]
	v_mfma_f32_16x16x32_bf16 v[10:13], v[146:149], v[238:241], v[10:13]
	s_setprio 0
	s_setprio 1
	v_mfma_f32_16x16x32_bf16 v[54:57], v[150:153], v[204:207], v[54:57]
	v_mfma_f32_16x16x32_bf16 v[54:57], v[154:157], v[208:211], v[54:57]
	v_mfma_f32_16x16x32_bf16 v[50:53], v[178:181], v[204:207], v[50:53]
	v_mfma_f32_16x16x32_bf16 v[50:53], v[186:189], v[208:211], v[50:53]
	v_mfma_f32_16x16x32_bf16 v[38:41], v[150:153], v[212:215], v[38:41]
	v_mfma_f32_16x16x32_bf16 v[38:41], v[154:157], v[216:219], v[38:41]
	v_mfma_f32_16x16x32_bf16 v[34:37], v[178:181], v[212:215], v[34:37]
	v_mfma_f32_16x16x32_bf16 v[34:37], v[186:189], v[216:219], v[34:37]
	v_mfma_f32_16x16x32_bf16 v[22:25], v[150:153], v[226:229], v[22:25]
	v_mfma_f32_16x16x32_bf16 v[22:25], v[154:157], v[230:233], v[22:25]
	v_mfma_f32_16x16x32_bf16 v[18:21], v[178:181], v[226:229], v[18:21]
	v_mfma_f32_16x16x32_bf16 v[18:21], v[186:189], v[230:233], v[18:21]
	v_mfma_f32_16x16x32_bf16 v[6:9], v[150:153], v[234:237], v[6:9]
	v_mfma_f32_16x16x32_bf16 v[6:9], v[154:157], v[238:241], v[6:9]
	v_mfma_f32_16x16x32_bf16 v[2:5], v[178:181], v[234:237], v[2:5]
	v_mfma_f32_16x16x32_bf16 v[2:5], v[186:189], v[238:241], v[2:5]
	s_setprio 0
	s_barrier
	s_add_i32 s72, 0, 0x18000
	s_add_i32 s74, 0, 0x1c000
	v_add_u32_e32 v146, s72, v184
	v_add_u32_e32 v186, s74, v184
	ds_read_b128 v[134:137], v146
	ds_read_b128 v[138:141], v146 offset:1024
	ds_read_b128 v[142:145], v146 offset:2048
	ds_read_b128 v[146:149], v146 offset:3072
	ds_read_b128 v[150:153], v186
	ds_read_b128 v[154:157], v186 offset:1024
	ds_read_b128 v[178:181], v186 offset:2048
	ds_read_b128 v[186:189], v186 offset:3072
	s_add_u32 s10, s10, s4
	s_addc_u32 s11, s11, s5
	s_mov_b32 m0, s16
	v_lshl_add_u64 v[248:249], s[10:11], 0, v[160:161]
	ds_read_b128 v[204:207], v185 offset:32768
	ds_read_b128 v[208:211], v185 offset:33792
	ds_read_b128 v[212:215], v185 offset:34816
	ds_read_b128 v[216:219], v185 offset:35840
	ds_read_b128 v[226:229], v185 offset:36864
	ds_read_b128 v[230:233], v185 offset:37888
	ds_read_b128 v[234:237], v185 offset:38912
	ds_read_b128 v[238:241], v185 offset:39936
	global_load_lds_dwordx4 v[248:249], off
	v_lshl_add_u64 v[248:249], s[10:11], 0, v[164:165]
	s_mov_b32 m0, s17
	s_nop 0
	global_load_lds_dwordx4 v[248:249], off
	s_waitcnt vmcnt(8)
	s_waitcnt lgkmcnt(0)
	s_barrier
	s_setprio 1
	s_waitcnt lgkmcnt(0)
	v_mfma_f32_16x16x32_bf16 v[126:129], v[134:137], v[204:207], v[126:129]
	v_mfma_f32_16x16x32_bf16 v[126:129], v[138:141], v[208:211], v[126:129]
	v_mfma_f32_16x16x32_bf16 v[122:125], v[142:145], v[204:207], v[122:125]
	v_mfma_f32_16x16x32_bf16 v[122:125], v[146:149], v[208:211], v[122:125]
	v_mfma_f32_16x16x32_bf16 v[110:113], v[134:137], v[212:215], v[110:113]
	v_mfma_f32_16x16x32_bf16 v[110:113], v[138:141], v[216:219], v[110:113]
	v_mfma_f32_16x16x32_bf16 v[106:109], v[142:145], v[212:215], v[106:109]
	v_mfma_f32_16x16x32_bf16 v[106:109], v[146:149], v[216:219], v[106:109]
	v_mfma_f32_16x16x32_bf16 v[94:97], v[134:137], v[226:229], v[94:97]
	v_mfma_f32_16x16x32_bf16 v[94:97], v[138:141], v[230:233], v[94:97]
	v_mfma_f32_16x16x32_bf16 v[90:93], v[142:145], v[226:229], v[90:93]
	v_mfma_f32_16x16x32_bf16 v[90:93], v[146:149], v[230:233], v[90:93]
	v_mfma_f32_16x16x32_bf16 v[78:81], v[134:137], v[234:237], v[78:81]
	v_mfma_f32_16x16x32_bf16 v[78:81], v[138:141], v[238:241], v[78:81]
	v_mfma_f32_16x16x32_bf16 v[74:77], v[142:145], v[234:237], v[74:77]
	v_mfma_f32_16x16x32_bf16 v[74:77], v[146:149], v[238:241], v[74:77]
	s_setprio 0
	s_setprio 1
	v_mfma_f32_16x16x32_bf16 v[118:121], v[150:153], v[204:207], v[118:121]
	v_mfma_f32_16x16x32_bf16 v[118:121], v[154:157], v[208:211], v[118:121]
	v_mfma_f32_16x16x32_bf16 v[114:117], v[178:181], v[204:207], v[114:117]
	v_mfma_f32_16x16x32_bf16 v[114:117], v[186:189], v[208:211], v[114:117]
	v_mfma_f32_16x16x32_bf16 v[102:105], v[150:153], v[212:215], v[102:105]
	v_mfma_f32_16x16x32_bf16 v[102:105], v[154:157], v[216:219], v[102:105]
	v_mfma_f32_16x16x32_bf16 v[98:101], v[178:181], v[212:215], v[98:101]
	v_mfma_f32_16x16x32_bf16 v[98:101], v[186:189], v[216:219], v[98:101]
	v_mfma_f32_16x16x32_bf16 v[86:89], v[150:153], v[226:229], v[86:89]
	v_mfma_f32_16x16x32_bf16 v[86:89], v[154:157], v[230:233], v[86:89]
	v_mfma_f32_16x16x32_bf16 v[82:85], v[178:181], v[226:229], v[82:85]
	v_mfma_f32_16x16x32_bf16 v[82:85], v[186:189], v[230:233], v[82:85]
	v_mfma_f32_16x16x32_bf16 v[70:73], v[150:153], v[234:237], v[70:73]
	v_mfma_f32_16x16x32_bf16 v[70:73], v[154:157], v[238:241], v[70:73]
	v_mfma_f32_16x16x32_bf16 v[66:69], v[178:181], v[234:237], v[66:69]
	v_mfma_f32_16x16x32_bf16 v[66:69], v[186:189], v[238:241], v[66:69]
	s_setprio 0
	s_barrier
	s_add_i32 s10, s72, s82
	v_lshl_add_u64 v[158:159], v[158:159], 0, s[68:69]
	s_mov_b32 m0, s10
	ds_read_b128 v[204:207], v185 offset:49152
	ds_read_b128 v[208:211], v185 offset:50176
	ds_read_b128 v[212:215], v185 offset:51200
	ds_read_b128 v[216:219], v185 offset:52224
	ds_read_b128 v[226:229], v185 offset:53248
	ds_read_b128 v[230:233], v185 offset:54272
	ds_read_b128 v[234:237], v185 offset:55296
	ds_read_b128 v[238:241], v185 offset:56320
	global_load_lds_dwordx4 v[158:159], off
	v_lshl_add_u64 v[158:159], v[182:183], 0, s[68:69]
	s_add_i32 m0, s10, 0x2000
	s_add_i32 s10, s74, s82
	global_load_lds_dwordx4 v[158:159], off
	v_lshl_add_u64 v[158:159], v[220:221], 0, s[68:69]
	s_mov_b32 m0, s10
	s_nop 0
	global_load_lds_dwordx4 v[158:159], off
	v_lshl_add_u64 v[158:159], v[242:243], 0, s[68:69]
	s_add_i32 m0, s10, 0x2000
	s_nop 0
	global_load_lds_dwordx4 v[158:159], off
	v_lshl_add_u64 v[158:159], v[244:245], 0, s[68:69]
	s_mov_b32 m0, s79
	s_nop 0
	global_load_lds_dwordx4 v[158:159], off
	v_lshl_add_u64 v[158:159], v[246:247], 0, s[68:69]
	s_mov_b32 m0, s78
	s_nop 0
	global_load_lds_dwordx4 v[158:159], off
	s_waitcnt vmcnt(8)
	s_waitcnt lgkmcnt(0)
	s_barrier
	s_setprio 1
	s_waitcnt lgkmcnt(0)
	v_mfma_f32_16x16x32_bf16 v[62:65], v[134:137], v[204:207], v[62:65]
	v_mfma_f32_16x16x32_bf16 v[62:65], v[138:141], v[208:211], v[62:65]
	v_mfma_f32_16x16x32_bf16 v[58:61], v[142:145], v[204:207], v[58:61]
	v_mfma_f32_16x16x32_bf16 v[58:61], v[146:149], v[208:211], v[58:61]
	v_mfma_f32_16x16x32_bf16 v[46:49], v[134:137], v[212:215], v[46:49]
	v_mfma_f32_16x16x32_bf16 v[46:49], v[138:141], v[216:219], v[46:49]
	v_mfma_f32_16x16x32_bf16 v[42:45], v[142:145], v[212:215], v[42:45]
	v_mfma_f32_16x16x32_bf16 v[42:45], v[146:149], v[216:219], v[42:45]
	v_mfma_f32_16x16x32_bf16 v[30:33], v[134:137], v[226:229], v[30:33]
	v_mfma_f32_16x16x32_bf16 v[30:33], v[138:141], v[230:233], v[30:33]
	v_mfma_f32_16x16x32_bf16 v[26:29], v[142:145], v[226:229], v[26:29]
	v_mfma_f32_16x16x32_bf16 v[26:29], v[146:149], v[230:233], v[26:29]
	v_mfma_f32_16x16x32_bf16 v[14:17], v[134:137], v[234:237], v[14:17]
	v_mfma_f32_16x16x32_bf16 v[14:17], v[138:141], v[238:241], v[14:17]
	v_mfma_f32_16x16x32_bf16 v[10:13], v[142:145], v[234:237], v[10:13]
	v_mfma_f32_16x16x32_bf16 v[10:13], v[146:149], v[238:241], v[10:13]
	s_setprio 0
	s_setprio 1
	v_mfma_f32_16x16x32_bf16 v[54:57], v[150:153], v[204:207], v[54:57]
	v_mfma_f32_16x16x32_bf16 v[54:57], v[154:157], v[208:211], v[54:57]
	v_mfma_f32_16x16x32_bf16 v[50:53], v[178:181], v[204:207], v[50:53]
	v_mfma_f32_16x16x32_bf16 v[50:53], v[186:189], v[208:211], v[50:53]
	v_mfma_f32_16x16x32_bf16 v[38:41], v[150:153], v[212:215], v[38:41]
	v_mfma_f32_16x16x32_bf16 v[38:41], v[154:157], v[216:219], v[38:41]
	v_mfma_f32_16x16x32_bf16 v[34:37], v[178:181], v[212:215], v[34:37]
	v_mfma_f32_16x16x32_bf16 v[34:37], v[186:189], v[216:219], v[34:37]
	v_mfma_f32_16x16x32_bf16 v[22:25], v[150:153], v[226:229], v[22:25]
	v_mfma_f32_16x16x32_bf16 v[22:25], v[154:157], v[230:233], v[22:25]
	v_mfma_f32_16x16x32_bf16 v[18:21], v[178:181], v[226:229], v[18:21]
	v_mfma_f32_16x16x32_bf16 v[18:21], v[186:189], v[230:233], v[18:21]
	v_mfma_f32_16x16x32_bf16 v[6:9], v[150:153], v[234:237], v[6:9]
	v_mfma_f32_16x16x32_bf16 v[6:9], v[154:157], v[238:241], v[6:9]
	v_mfma_f32_16x16x32_bf16 v[2:5], v[178:181], v[234:237], v[2:5]
	v_mfma_f32_16x16x32_bf16 v[2:5], v[186:189], v[238:241], v[2:5]
	s_setprio 0
	s_barrier
	s_add_i32 s49, s49, 2
	s_add_u32 s44, s44, 0x100
	s_addc_u32 s45, s45, 0
	s_cmp_gt_u32 s49, 13
	s_cbranch_scc0 .LBB0_1658
	s_and_b64 vcc, exec, s[24:25]
	s_cbranch_vccz .LBB0_1661
	s_barrier

.LBB0_1766:
	s_add_i32 s82, s26, 2
	s_add_u32 s74, s24, 0x80
	s_addc_u32 s27, s25, 0
	s_add_i32 s85, 0, 0x10000
	s_cmp_eq_u32 s19, s26
	s_cselect_b32 s27, s21, s27
	s_cselect_b32 s26, s20, s74
	v_add_u32_e32 v148, s85, v152
	s_cselect_b32 s75, s23, s29
	s_cselect_b32 s74, s22, s28
	s_add_i32 s86, 0, 0x14000
	ds_read_b128 v[130:133], v148
	ds_read_b128 v[144:147], v148 offset:1024
	ds_read_b128 v[154:157], v148 offset:2048
	ds_read_b128 v[158:161], v148 offset:3072
	v_add_u32_e32 v148, s86, v152
	ds_read_b128 v[162:165], v148
	ds_read_b128 v[166:169], v148 offset:1024
	ds_read_b128 v[170:173], v148 offset:2048
	ds_read_b128 v[174:177], v148 offset:3072
	v_lshl_add_u64 v[148:149], s[24:25], 0, v[140:141]
	s_add_i32 m0, s34, 0xc000
	ds_read_b128 v[178:181], v153
	ds_read_b128 v[182:185], v153 offset:1024
	ds_read_b128 v[186:189], v153 offset:2048
	ds_read_b128 v[204:207], v153 offset:3072
	ds_read_b128 v[208:211], v153 offset:4096
	ds_read_b128 v[212:215], v153 offset:5120
	ds_read_b128 v[216:219], v153 offset:6144
	ds_read_b128 v[226:229], v153 offset:7168
	global_load_lds_dwordx4 v[148:149], off
	v_lshl_add_u64 v[148:149], s[24:25], 0, v[142:143]
	s_add_i32 m0, s34, 0xe000
	s_nop 0
	global_load_lds_dwordx4 v[148:149], off
	s_waitcnt vmcnt(8)
	s_waitcnt lgkmcnt(0)
	s_barrier
	s_setprio 1
	s_waitcnt lgkmcnt(0)
	v_mfma_f32_16x16x32_bf16 v[126:129], v[130:133], v[178:181], v[126:129]
	v_mfma_f32_16x16x32_bf16 v[126:129], v[144:147], v[182:185], v[126:129]
	v_mfma_f32_16x16x32_bf16 v[122:125], v[154:157], v[178:181], v[122:125]
	v_mfma_f32_16x16x32_bf16 v[122:125], v[158:161], v[182:185], v[122:125]
	v_mfma_f32_16x16x32_bf16 v[110:113], v[130:133], v[186:189], v[110:113]
	v_mfma_f32_16x16x32_bf16 v[110:113], v[144:147], v[204:207], v[110:113]
	v_mfma_f32_16x16x32_bf16 v[106:109], v[154:157], v[186:189], v[106:109]
	v_mfma_f32_16x16x32_bf16 v[106:109], v[158:161], v[204:207], v[106:109]
	v_mfma_f32_16x16x32_bf16 v[94:97], v[130:133], v[208:211], v[94:97]
	v_mfma_f32_16x16x32_bf16 v[94:97], v[144:147], v[212:215], v[94:97]
	v_mfma_f32_16x16x32_bf16 v[90:93], v[154:157], v[208:211], v[90:93]
	v_mfma_f32_16x16x32_bf16 v[90:93], v[158:161], v[212:215], v[90:93]
	v_mfma_f32_16x16x32_bf16 v[78:81], v[130:133], v[216:219], v[78:81]
	v_mfma_f32_16x16x32_bf16 v[78:81], v[144:147], v[226:229], v[78:81]
	v_mfma_f32_16x16x32_bf16 v[74:77], v[154:157], v[216:219], v[74:77]
	v_mfma_f32_16x16x32_bf16 v[74:77], v[158:161], v[226:229], v[74:77]
	s_setprio 0
	s_setprio 1
	v_mfma_f32_16x16x32_bf16 v[118:121], v[162:165], v[178:181], v[118:121]
	v_mfma_f32_16x16x32_bf16 v[118:121], v[166:169], v[182:185], v[118:121]
	v_mfma_f32_16x16x32_bf16 v[114:117], v[170:173], v[178:181], v[114:117]
	v_mfma_f32_16x16x32_bf16 v[114:117], v[174:177], v[182:185], v[114:117]
	v_mfma_f32_16x16x32_bf16 v[102:105], v[162:165], v[186:189], v[102:105]
	v_mfma_f32_16x16x32_bf16 v[102:105], v[166:169], v[204:207], v[102:105]
	v_mfma_f32_16x16x32_bf16 v[98:101], v[170:173], v[186:189], v[98:101]
	v_mfma_f32_16x16x32_bf16 v[98:101], v[174:177], v[204:207], v[98:101]
	v_mfma_f32_16x16x32_bf16 v[86:89], v[162:165], v[208:211], v[86:89]
	v_mfma_f32_16x16x32_bf16 v[86:89], v[166:169], v[212:215], v[86:89]
	v_mfma_f32_16x16x32_bf16 v[82:85], v[170:173], v[208:211], v[82:85]
	v_mfma_f32_16x16x32_bf16 v[82:85], v[174:177], v[212:215], v[82:85]
	v_mfma_f32_16x16x32_bf16 v[70:73], v[162:165], v[216:219], v[70:73]
	v_mfma_f32_16x16x32_bf16 v[70:73], v[166:169], v[226:229], v[70:73]
	v_mfma_f32_16x16x32_bf16 v[66:69], v[170:173], v[216:219], v[66:69]
	v_mfma_f32_16x16x32_bf16 v[66:69], v[174:177], v[226:229], v[66:69]
	s_setprio 0
	s_barrier
	s_add_i32 s85, s85, s33
	v_lshl_add_u64 v[148:149], s[74:75], 0, v[190:191]
	s_mov_b32 m0, s85
	ds_read_b128 v[178:181], v153 offset:16384
	ds_read_b128 v[182:185], v153 offset:17408
	ds_read_b128 v[186:189], v153 offset:18432
	ds_read_b128 v[204:207], v153 offset:19456
	ds_read_b128 v[208:211], v153 offset:20480
	ds_read_b128 v[212:215], v153 offset:21504
	ds_read_b128 v[216:219], v153 offset:22528
	ds_read_b128 v[226:229], v153 offset:23552
	global_load_lds_dwordx4 v[148:149], off
	s_add_i32 m0, s85, 0x2000
	v_lshl_add_u64 v[220:221], s[74:75], 0, v[138:139]
	s_add_u32 s74, s74, s8
	s_addc_u32 s75, s75, s9
	s_add_i32 s85, s86, s33
	global_load_lds_dwordx4 v[220:221], off
	v_lshl_add_u64 v[230:231], s[74:75], 0, v[190:191]
	s_mov_b32 m0, s85
	v_lshl_add_u64 v[232:233], s[74:75], 0, v[138:139]
	global_load_lds_dwordx4 v[230:231], off
	s_add_i32 m0, s85, 0x2000
	v_lshl_add_u64 v[234:235], s[26:27], 0, v[134:135]
	global_load_lds_dwordx4 v[232:233], off
	s_mov_b32 m0, s34
	v_lshl_add_u64 v[236:237], s[26:27], 0, v[136:137]
	global_load_lds_dwordx4 v[234:235], off
	s_mov_b32 m0, s35
	s_nop 0
	global_load_lds_dwordx4 v[236:237], off
	s_waitcnt vmcnt(8)
	s_waitcnt lgkmcnt(0)
	s_barrier
	s_setprio 1
	s_waitcnt lgkmcnt(0)
	v_mfma_f32_16x16x32_bf16 v[62:65], v[130:133], v[178:181], v[62:65]
	v_mfma_f32_16x16x32_bf16 v[62:65], v[144:147], v[182:185], v[62:65]
	v_mfma_f32_16x16x32_bf16 v[58:61], v[154:157], v[178:181], v[58:61]
	v_mfma_f32_16x16x32_bf16 v[58:61], v[158:161], v[182:185], v[58:61]
	v_mfma_f32_16x16x32_bf16 v[46:49], v[130:133], v[186:189], v[46:49]
	v_mfma_f32_16x16x32_bf16 v[46:49], v[144:147], v[204:207], v[46:49]
	v_mfma_f32_16x16x32_bf16 v[42:45], v[154:157], v[186:189], v[42:45]
	v_mfma_f32_16x16x32_bf16 v[42:45], v[158:161], v[204:207], v[42:45]
	v_mfma_f32_16x16x32_bf16 v[30:33], v[130:133], v[208:211], v[30:33]
	v_mfma_f32_16x16x32_bf16 v[30:33], v[144:147], v[212:215], v[30:33]
	v_mfma_f32_16x16x32_bf16 v[26:29], v[154:157], v[208:211], v[26:29]
	v_mfma_f32_16x16x32_bf16 v[26:29], v[158:161], v[212:215], v[26:29]
	v_mfma_f32_16x16x32_bf16 v[14:17], v[130:133], v[216:219], v[14:17]
	v_mfma_f32_16x16x32_bf16 v[14:17], v[144:147], v[226:229], v[14:17]
	v_mfma_f32_16x16x32_bf16 v[10:13], v[154:157], v[216:219], v[10:13]
	v_mfma_f32_16x16x32_bf16 v[10:13], v[158:161], v[226:229], v[10:13]
	s_setprio 0
	s_setprio 1
	v_mfma_f32_16x16x32_bf16 v[54:57], v[162:165], v[178:181], v[54:57]
	v_mfma_f32_16x16x32_bf16 v[54:57], v[166:169], v[182:185], v[54:57]
	v_mfma_f32_16x16x32_bf16 v[50:53], v[170:173], v[178:181], v[50:53]
	v_mfma_f32_16x16x32_bf16 v[50:53], v[174:177], v[182:185], v[50:53]
	v_mfma_f32_16x16x32_bf16 v[38:41], v[162:165], v[186:189], v[38:41]
	v_mfma_f32_16x16x32_bf16 v[38:41], v[166:169], v[204:207], v[38:41]
	v_mfma_f32_16x16x32_bf16 v[34:37], v[170:173], v[186:189], v[34:37]
	v_mfma_f32_16x16x32_bf16 v[34:37], v[174:177], v[204:207], v[34:37]
	v_mfma_f32_16x16x32_bf16 v[22:25], v[162:165], v[208:211], v[22:25]
	v_mfma_f32_16x16x32_bf16 v[22:25], v[166:169], v[212:215], v[22:25]
	v_mfma_f32_16x16x32_bf16 v[18:21], v[170:173], v[208:211], v[18:21]
	v_mfma_f32_16x16x32_bf16 v[18:21], v[174:177], v[212:215], v[18:21]
	v_mfma_f32_16x16x32_bf16 v[6:9], v[162:165], v[216:219], v[6:9]
	v_mfma_f32_16x16x32_bf16 v[6:9], v[166:169], v[226:229], v[6:9]
	v_mfma_f32_16x16x32_bf16 v[2:5], v[170:173], v[216:219], v[2:5]
	v_mfma_f32_16x16x32_bf16 v[2:5], v[174:177], v[226:229], v[2:5]
	s_setprio 0
	s_barrier
	s_add_i32 s74, 0, 0x18000
	s_add_i32 s75, 0, 0x1c000
	v_add_u32_e32 v158, s74, v152
	v_add_u32_e32 v174, s75, v152
	ds_read_b128 v[130:133], v158
	ds_read_b128 v[144:147], v158 offset:1024
	ds_read_b128 v[154:157], v158 offset:2048
	ds_read_b128 v[158:161], v158 offset:3072
	ds_read_b128 v[162:165], v174
	ds_read_b128 v[166:169], v174 offset:1024
	ds_read_b128 v[170:173], v174 offset:2048
	ds_read_b128 v[174:177], v174 offset:3072
	s_add_u32 s26, s26, s8
	s_addc_u32 s27, s27, s9
	s_mov_b32 m0, s36
	v_lshl_add_u64 v[238:239], s[26:27], 0, v[134:135]
	ds_read_b128 v[178:181], v153 offset:32768
	ds_read_b128 v[182:185], v153 offset:33792
	ds_read_b128 v[186:189], v153 offset:34816
	ds_read_b128 v[204:207], v153 offset:35840
	ds_read_b128 v[208:211], v153 offset:36864
	ds_read_b128 v[212:215], v153 offset:37888
	ds_read_b128 v[216:219], v153 offset:38912
	ds_read_b128 v[226:229], v153 offset:39936
	global_load_lds_dwordx4 v[238:239], off
	v_lshl_add_u64 v[238:239], s[26:27], 0, v[136:137]
	s_mov_b32 m0, s37
	s_nop 0
	global_load_lds_dwordx4 v[238:239], off
	s_waitcnt vmcnt(8)
	s_waitcnt lgkmcnt(0)
	s_barrier
	s_setprio 1
	s_waitcnt lgkmcnt(0)
	v_mfma_f32_16x16x32_bf16 v[126:129], v[130:133], v[178:181], v[126:129]
	v_mfma_f32_16x16x32_bf16 v[126:129], v[144:147], v[182:185], v[126:129]
	v_mfma_f32_16x16x32_bf16 v[122:125], v[154:157], v[178:181], v[122:125]
	v_mfma_f32_16x16x32_bf16 v[122:125], v[158:161], v[182:185], v[122:125]
	v_mfma_f32_16x16x32_bf16 v[110:113], v[130:133], v[186:189], v[110:113]
	v_mfma_f32_16x16x32_bf16 v[110:113], v[144:147], v[204:207], v[110:113]
	v_mfma_f32_16x16x32_bf16 v[106:109], v[154:157], v[186:189], v[106:109]
	v_mfma_f32_16x16x32_bf16 v[106:109], v[158:161], v[204:207], v[106:109]
	v_mfma_f32_16x16x32_bf16 v[94:97], v[130:133], v[208:211], v[94:97]
	v_mfma_f32_16x16x32_bf16 v[94:97], v[144:147], v[212:215], v[94:97]
	v_mfma_f32_16x16x32_bf16 v[90:93], v[154:157], v[208:211], v[90:93]
	v_mfma_f32_16x16x32_bf16 v[90:93], v[158:161], v[212:215], v[90:93]
	v_mfma_f32_16x16x32_bf16 v[78:81], v[130:133], v[216:219], v[78:81]
	v_mfma_f32_16x16x32_bf16 v[78:81], v[144:147], v[226:229], v[78:81]
	v_mfma_f32_16x16x32_bf16 v[74:77], v[154:157], v[216:219], v[74:77]
	v_mfma_f32_16x16x32_bf16 v[74:77], v[158:161], v[226:229], v[74:77]
	s_setprio 0
	s_setprio 1
	v_mfma_f32_16x16x32_bf16 v[118:121], v[162:165], v[178:181], v[118:121]
	v_mfma_f32_16x16x32_bf16 v[118:121], v[166:169], v[182:185], v[118:121]
	v_mfma_f32_16x16x32_bf16 v[114:117], v[170:173], v[178:181], v[114:117]
	v_mfma_f32_16x16x32_bf16 v[114:117], v[174:177], v[182:185], v[114:117]
	v_mfma_f32_16x16x32_bf16 v[102:105], v[162:165], v[186:189], v[102:105]
	v_mfma_f32_16x16x32_bf16 v[102:105], v[166:169], v[204:207], v[102:105]
	v_mfma_f32_16x16x32_bf16 v[98:101], v[170:173], v[186:189], v[98:101]
	v_mfma_f32_16x16x32_bf16 v[98:101], v[174:177], v[204:207], v[98:101]
	v_mfma_f32_16x16x32_bf16 v[86:89], v[162:165], v[208:211], v[86:89]
	v_mfma_f32_16x16x32_bf16 v[86:89], v[166:169], v[212:215], v[86:89]
	v_mfma_f32_16x16x32_bf16 v[82:85], v[170:173], v[208:211], v[82:85]
	v_mfma_f32_16x16x32_bf16 v[82:85], v[174:177], v[212:215], v[82:85]
	v_mfma_f32_16x16x32_bf16 v[70:73], v[162:165], v[216:219], v[70:73]
	v_mfma_f32_16x16x32_bf16 v[70:73], v[166:169], v[226:229], v[70:73]
	v_mfma_f32_16x16x32_bf16 v[66:69], v[170:173], v[216:219], v[66:69]
	v_mfma_f32_16x16x32_bf16 v[66:69], v[174:177], v[226:229], v[66:69]
	s_setprio 0
	s_barrier
	s_add_i32 s26, s74, s33
	v_lshl_add_u64 v[148:149], v[148:149], 0, s[68:69]
	s_mov_b32 m0, s26
	ds_read_b128 v[178:181], v153 offset:49152
	ds_read_b128 v[182:185], v153 offset:50176
	ds_read_b128 v[186:189], v153 offset:51200
	ds_read_b128 v[204:207], v153 offset:52224
	ds_read_b128 v[208:211], v153 offset:53248
	ds_read_b128 v[212:215], v153 offset:54272
	ds_read_b128 v[216:219], v153 offset:55296
	ds_read_b128 v[226:229], v153 offset:56320
	global_load_lds_dwordx4 v[148:149], off
	v_lshl_add_u64 v[148:149], v[220:221], 0, s[68:69]
	s_add_i32 m0, s26, 0x2000
	s_add_i32 s26, s75, s33
	global_load_lds_dwordx4 v[148:149], off
	v_lshl_add_u64 v[148:149], v[230:231], 0, s[68:69]
	s_mov_b32 m0, s26
	s_nop 0
	global_load_lds_dwordx4 v[148:149], off
	v_lshl_add_u64 v[148:149], v[232:233], 0, s[68:69]
	s_add_i32 m0, s26, 0x2000
	s_nop 0
	global_load_lds_dwordx4 v[148:149], off
	v_lshl_add_u64 v[148:149], v[234:235], 0, s[68:69]
	s_mov_b32 m0, s59
	s_nop 0
	global_load_lds_dwordx4 v[148:149], off
	v_lshl_add_u64 v[148:149], v[236:237], 0, s[68:69]
	s_mov_b32 m0, s64
	s_nop 0
	global_load_lds_dwordx4 v[148:149], off
	s_waitcnt vmcnt(8)
	s_waitcnt lgkmcnt(0)
	s_barrier
	s_setprio 1
	s_waitcnt lgkmcnt(0)
	v_mfma_f32_16x16x32_bf16 v[62:65], v[130:133], v[178:181], v[62:65]
	v_mfma_f32_16x16x32_bf16 v[62:65], v[144:147], v[182:185], v[62:65]
	v_mfma_f32_16x16x32_bf16 v[58:61], v[154:157], v[178:181], v[58:61]
	v_mfma_f32_16x16x32_bf16 v[58:61], v[158:161], v[182:185], v[58:61]
	v_mfma_f32_16x16x32_bf16 v[46:49], v[130:133], v[186:189], v[46:49]
	v_mfma_f32_16x16x32_bf16 v[46:49], v[144:147], v[204:207], v[46:49]
	v_mfma_f32_16x16x32_bf16 v[42:45], v[154:157], v[186:189], v[42:45]
	v_mfma_f32_16x16x32_bf16 v[42:45], v[158:161], v[204:207], v[42:45]
	v_mfma_f32_16x16x32_bf16 v[30:33], v[130:133], v[208:211], v[30:33]
	v_mfma_f32_16x16x32_bf16 v[30:33], v[144:147], v[212:215], v[30:33]
	v_mfma_f32_16x16x32_bf16 v[26:29], v[154:157], v[208:211], v[26:29]
	v_mfma_f32_16x16x32_bf16 v[26:29], v[158:161], v[212:215], v[26:29]
	v_mfma_f32_16x16x32_bf16 v[14:17], v[130:133], v[216:219], v[14:17]
	v_mfma_f32_16x16x32_bf16 v[14:17], v[144:147], v[226:229], v[14:17]
	v_mfma_f32_16x16x32_bf16 v[10:13], v[154:157], v[216:219], v[10:13]
	v_mfma_f32_16x16x32_bf16 v[10:13], v[158:161], v[226:229], v[10:13]
	s_setprio 0
	s_setprio 1
	v_mfma_f32_16x16x32_bf16 v[54:57], v[162:165], v[178:181], v[54:57]
	v_mfma_f32_16x16x32_bf16 v[54:57], v[166:169], v[182:185], v[54:57]
	v_mfma_f32_16x16x32_bf16 v[50:53], v[170:173], v[178:181], v[50:53]
	v_mfma_f32_16x16x32_bf16 v[50:53], v[174:177], v[182:185], v[50:53]
	v_mfma_f32_16x16x32_bf16 v[38:41], v[162:165], v[186:189], v[38:41]
	v_mfma_f32_16x16x32_bf16 v[38:41], v[166:169], v[204:207], v[38:41]
	v_mfma_f32_16x16x32_bf16 v[34:37], v[170:173], v[186:189], v[34:37]
	v_mfma_f32_16x16x32_bf16 v[34:37], v[174:177], v[204:207], v[34:37]
	v_mfma_f32_16x16x32_bf16 v[22:25], v[162:165], v[208:211], v[22:25]
	v_mfma_f32_16x16x32_bf16 v[22:25], v[166:169], v[212:215], v[22:25]
	v_mfma_f32_16x16x32_bf16 v[18:21], v[170:173], v[208:211], v[18:21]
	v_mfma_f32_16x16x32_bf16 v[18:21], v[174:177], v[212:215], v[18:21]
	v_mfma_f32_16x16x32_bf16 v[6:9], v[162:165], v[216:219], v[6:9]
	v_mfma_f32_16x16x32_bf16 v[6:9], v[166:169], v[226:229], v[6:9]
	v_mfma_f32_16x16x32_bf16 v[2:5], v[170:173], v[216:219], v[2:5]
	v_mfma_f32_16x16x32_bf16 v[2:5], v[174:177], v[226:229], v[2:5]
	s_setprio 0
	s_barrier
	s_add_u32 s24, s24, 0x100
	s_addc_u32 s25, s25, 0
	s_add_u32 s28, s28, 0x100
	s_addc_u32 s29, s29, 0
	s_cmp_ge_i32 s82, s81
	s_mov_b32 s26, s82
	s_cbranch_scc0 .LBB0_1766
	s_and_b64 vcc, exec, s[14:15]
	s_cbranch_vccz .LBB0_1769
	s_barrier
